# PROJ GEMM: 256x128 block tile with own fp16 / v-transposed / gate-preactivation epilogues
# speedup vs baseline: 1.5090x; 1.0177x over previous
.LBB0_217:
	s_add_i32 s21, s21, s20
	s_lshr_b32 s1, s61, 1
	s_cmp_lt_i32 s21, s1
	s_cbranch_scc0 .LBB0_247

.LBB0_221:
	s_sub_u32 s0, s38, s65
	s_lshl_b32 s0, s0, 8
	s_lshl_b32 s12, s65, 7
	s_add_u32 s0, s0, s12
	s_lshl_b32 s23, s22, 7
	v_lshrrev_b32_e32 v132, 4, v182
	v_xor_b32_e32 v132, v132, v182
	v_and_b32_e32 v132, 7, v132
	v_lshlrev_b32_e32 v132, 4, v132
	v_lshrrev_b32_e32 v133, 3, v182
	v_lshrrev_b32_e32 v134, 6, v182
	v_mul_u32_u24_e32 v180, 0x800, v133
	v_readfirstlane_b32 s12, v134
	v_add_u32_e32 v180, v180, v132
	v_and_b32_e32 v135, 15, v182
	v_bfe_u32 v136, v182, 4, 2
	v_bfe_u32 v137, v182, 1, 3
	v_xor_b32_e32 v138, v136, v137
	v_or_b32_e32 v139, 4, v136
	v_xor_b32_e32 v139, v139, v137
	v_lshlrev_b32_e32 v138, 4, v138
	v_lshlrev_b32_e32 v139, 4, v139
	v_lshl_or_b32 v138, v135, 7, v138
	v_lshl_or_b32 v139, v135, 7, v139
	v_bfe_u32 v140, v182, 7, 1
	v_bfe_u32 v141, v182, 6, 1
	v_lshl_add_u32 v181, v140, 14, v138
	v_lshl_add_u32 v208, v140, 14, v139
	v_lshl_add_u32 v223, v141, 13, v138
	v_lshl_add_u32 v233, v141, 13, v139
	s_lshl_b32 s12, s12, 10
	s_mul_hi_u32 s14, s0, 0x800
	s_mul_i32 s13, s0, 0x800
	s_add_u32 s2, s40, s13
	s_addc_u32 s3, s41, s14
	s_mul_hi_u32 s14, s23, 0x800
	s_mul_i32 s13, s23, 0x800
	v_readlane_b32 s6, v251, 23
	v_readlane_b32 s7, v251, 24
	s_add_u32 s6, s6, s13
	s_addc_u32 s7, s7, s14
	s_mov_b32 s16, 0x8000
	s_add_u32 m0, s12, 0x0
	s_nop 0
	global_load_lds_dwordx4 v180, s[2:3]
	s_add_u32 m0, s12, 0x1000
	s_add_u32 s4, s2, 0x10000
	s_addc_u32 s5, s3, 0
	global_load_lds_dwordx4 v180, s[4:5]
	s_add_u32 m0, s12, 0x2000
	s_add_u32 s4, s2, 0x20000
	s_addc_u32 s5, s3, 0
	global_load_lds_dwordx4 v180, s[4:5]
	s_add_u32 m0, s12, 0x3000
	s_add_u32 s4, s2, 0x30000
	s_addc_u32 s5, s3, 0
	global_load_lds_dwordx4 v180, s[4:5]
	s_add_u32 m0, s12, 0x4000
	s_add_u32 s4, s2, 0x40000
	s_addc_u32 s5, s3, 0
	global_load_lds_dwordx4 v180, s[4:5]
	s_add_u32 m0, s12, 0x5000
	s_add_u32 s4, s2, 0x50000
	s_addc_u32 s5, s3, 0
	global_load_lds_dwordx4 v180, s[4:5]
	s_add_u32 m0, s12, 0x6000
	s_add_u32 s4, s2, 0x60000
	s_addc_u32 s5, s3, 0
	global_load_lds_dwordx4 v180, s[4:5]
	s_add_u32 m0, s12, 0x7000
	s_add_u32 s4, s2, 0x70000
	s_addc_u32 s5, s3, 0
	global_load_lds_dwordx4 v180, s[4:5]
	s_add_u32 s2, s2, 0x80
	s_addc_u32 s3, s3, 0
	s_add_u32 m0, s12, s16
	s_nop 0
	global_load_lds_dwordx4 v180, s[6:7]
	s_add_u32 m0, m0, 0x1000
	s_add_u32 s4, s6, 0x10000
	s_addc_u32 s5, s7, 0
	global_load_lds_dwordx4 v180, s[4:5]
	s_add_u32 m0, m0, 0x1000
	s_add_u32 s4, s6, 0x20000
	s_addc_u32 s5, s7, 0
	global_load_lds_dwordx4 v180, s[4:5]
	s_add_u32 m0, m0, 0x1000
	s_add_u32 s4, s6, 0x30000
	s_addc_u32 s5, s7, 0
	global_load_lds_dwordx4 v180, s[4:5]
	s_add_u32 s6, s6, 0x80
	s_addc_u32 s7, s7, 0
	v_mov_b32_e32 v0, 0
	v_mov_b32_e32 v1, v0
	v_mov_b32_e32 v2, v0
	v_mov_b32_e32 v3, v0
	v_mov_b32_e32 v4, v0
	v_mov_b32_e32 v5, v0
	v_mov_b32_e32 v6, v0
	v_mov_b32_e32 v7, v0
	v_mov_b32_e32 v8, v0
	v_mov_b32_e32 v9, v0
	v_mov_b32_e32 v10, v0
	v_mov_b32_e32 v11, v0
	v_mov_b32_e32 v12, v0
	v_mov_b32_e32 v13, v0
	v_mov_b32_e32 v14, v0
	v_mov_b32_e32 v15, v0
	v_mov_b32_e32 v16, v0
	v_mov_b32_e32 v17, v0
	v_mov_b32_e32 v18, v0
	v_mov_b32_e32 v19, v0
	v_mov_b32_e32 v20, v0
	v_mov_b32_e32 v21, v0
	v_mov_b32_e32 v22, v0
	v_mov_b32_e32 v23, v0
	v_mov_b32_e32 v24, v0
	v_mov_b32_e32 v25, v0
	v_mov_b32_e32 v26, v0
	v_mov_b32_e32 v27, v0
	v_mov_b32_e32 v28, v0
	v_mov_b32_e32 v29, v0
	v_mov_b32_e32 v30, v0
	v_mov_b32_e32 v31, v0
	v_mov_b32_e32 v32, v0
	v_mov_b32_e32 v33, v0
	v_mov_b32_e32 v34, v0
	v_mov_b32_e32 v35, v0
	v_mov_b32_e32 v36, v0
	v_mov_b32_e32 v37, v0
	v_mov_b32_e32 v38, v0
	v_mov_b32_e32 v39, v0
	v_mov_b32_e32 v40, v0
	v_mov_b32_e32 v41, v0
	v_mov_b32_e32 v42, v0
	v_mov_b32_e32 v43, v0
	v_mov_b32_e32 v44, v0
	v_mov_b32_e32 v45, v0
	v_mov_b32_e32 v46, v0
	v_mov_b32_e32 v47, v0
	v_mov_b32_e32 v48, v0
	v_mov_b32_e32 v49, v0
	v_mov_b32_e32 v50, v0
	v_mov_b32_e32 v51, v0
	v_mov_b32_e32 v52, v0
	v_mov_b32_e32 v53, v0
	v_mov_b32_e32 v54, v0
	v_mov_b32_e32 v55, v0
	v_mov_b32_e32 v56, v0
	v_mov_b32_e32 v57, v0
	v_mov_b32_e32 v58, v0
	v_mov_b32_e32 v59, v0
	v_mov_b32_e32 v60, v0
	v_mov_b32_e32 v61, v0
	v_mov_b32_e32 v62, v0
	v_mov_b32_e32 v63, v0
	v_mov_b32_e32 v64, v0
	v_mov_b32_e32 v65, v0
	v_mov_b32_e32 v66, v0
	v_mov_b32_e32 v67, v0
	v_mov_b32_e32 v68, v0
	v_mov_b32_e32 v69, v0
	v_mov_b32_e32 v70, v0
	v_mov_b32_e32 v71, v0
	v_mov_b32_e32 v72, v0
	v_mov_b32_e32 v73, v0
	v_mov_b32_e32 v74, v0
	v_mov_b32_e32 v75, v0
	v_mov_b32_e32 v76, v0
	v_mov_b32_e32 v77, v0
	v_mov_b32_e32 v78, v0
	v_mov_b32_e32 v79, v0
	v_mov_b32_e32 v80, v0
	v_mov_b32_e32 v81, v0
	v_mov_b32_e32 v82, v0
	v_mov_b32_e32 v83, v0
	v_mov_b32_e32 v84, v0
	v_mov_b32_e32 v85, v0
	v_mov_b32_e32 v86, v0
	v_mov_b32_e32 v87, v0
	v_mov_b32_e32 v88, v0
	v_mov_b32_e32 v89, v0
	v_mov_b32_e32 v90, v0
	v_mov_b32_e32 v91, v0
	v_mov_b32_e32 v92, v0
	v_mov_b32_e32 v93, v0
	v_mov_b32_e32 v94, v0
	v_mov_b32_e32 v95, v0
	v_mov_b32_e32 v96, v0
	v_mov_b32_e32 v97, v0
	v_mov_b32_e32 v98, v0
	v_mov_b32_e32 v99, v0
	v_mov_b32_e32 v100, v0
	v_mov_b32_e32 v101, v0
	v_mov_b32_e32 v102, v0
	v_mov_b32_e32 v103, v0
	v_mov_b32_e32 v104, v0
	v_mov_b32_e32 v105, v0
	v_mov_b32_e32 v106, v0
	v_mov_b32_e32 v107, v0
	v_mov_b32_e32 v108, v0
	v_mov_b32_e32 v109, v0
	v_mov_b32_e32 v110, v0
	v_mov_b32_e32 v111, v0
	v_mov_b32_e32 v116, v0
	v_mov_b32_e32 v117, v0
	v_mov_b32_e32 v118, v0
	v_mov_b32_e32 v119, v0
	v_mov_b32_e32 v120, v0
	v_mov_b32_e32 v121, v0
	v_mov_b32_e32 v122, v0
	v_mov_b32_e32 v123, v0
	v_mov_b32_e32 v124, v0
	v_mov_b32_e32 v125, v0
	v_mov_b32_e32 v126, v0
	v_mov_b32_e32 v127, v0
	v_mov_b32_e32 v128, v0
	v_mov_b32_e32 v129, v0
	v_mov_b32_e32 v130, v0
	v_mov_b32_e32 v131, v0
	s_movk_i32 s15, 15
.Lg4_pj:
	s_waitcnt vmcnt(0)
	s_barrier
	s_xor_b32 s16, s16, 0x4000
	s_cmp_eq_u32 s15, 0
	s_cbranch_scc1 .Lg4_pj_nb
	s_add_u32 m0, s12, s16
	s_nop 0
	global_load_lds_dwordx4 v180, s[6:7]
	s_add_u32 m0, m0, 0x1000
	s_add_u32 s4, s6, 0x10000
	s_addc_u32 s5, s7, 0
	global_load_lds_dwordx4 v180, s[4:5]
	s_add_u32 m0, m0, 0x1000
	s_add_u32 s4, s6, 0x20000
	s_addc_u32 s5, s7, 0
	global_load_lds_dwordx4 v180, s[4:5]
	s_add_u32 m0, m0, 0x1000
	s_add_u32 s4, s6, 0x30000
	s_addc_u32 s5, s7, 0
	global_load_lds_dwordx4 v180, s[4:5]
	s_add_u32 s6, s6, 0x80
	s_addc_u32 s7, s7, 0
.Lg4_pj_nb:
	ds_read_b128 v[132:135], v181 offset:0
	ds_read_b128 v[136:139], v181 offset:2048
	ds_read_b128 v[140:143], v181 offset:4096
	ds_read_b128 v[144:147], v181 offset:6144
	ds_read_b128 v[148:151], v181 offset:8192
	ds_read_b128 v[152:155], v181 offset:10240
	ds_read_b128 v[156:159], v181 offset:12288
	ds_read_b128 v[160:163], v181 offset:14336
	ds_read_b128 v[164:167], v208 offset:0
	ds_read_b128 v[168:171], v208 offset:2048
	ds_read_b128 v[172:175], v208 offset:4096
	ds_read_b128 v[176:179], v208 offset:6144
	ds_read_b128 v[224:227], v208 offset:8192
	ds_read_b128 v[228:231], v208 offset:10240
	s_waitcnt lgkmcnt(6)
	ds_read_b128 v[234:237], v208 offset:12288
	ds_read_b128 v[238:241], v208 offset:14336
	ds_read_b128 v[242:245], v223 offset:32768
	ds_read_b128 v[112:115], v223 offset:34816
	s_waitcnt lgkmcnt(2)
	s_barrier
	s_cmp_eq_u32 s15, 0
	s_cbranch_scc1 .Lg4_pj_nl
	s_add_u32 m0, s12, 0x0
	s_nop 0
	global_load_lds_dwordx4 v180, s[2:3]
	s_add_u32 m0, s12, 0x1000
	s_add_u32 s4, s2, 0x10000
	s_addc_u32 s5, s3, 0
	global_load_lds_dwordx4 v180, s[4:5]
	s_add_u32 m0, s12, 0x2000
	s_add_u32 s4, s2, 0x20000
	s_addc_u32 s5, s3, 0
	global_load_lds_dwordx4 v180, s[4:5]
	s_add_u32 m0, s12, 0x3000
	s_add_u32 s4, s2, 0x30000
	s_addc_u32 s5, s3, 0
	global_load_lds_dwordx4 v180, s[4:5]
	s_add_u32 m0, s12, 0x4000
	s_add_u32 s4, s2, 0x40000
	s_addc_u32 s5, s3, 0
	global_load_lds_dwordx4 v180, s[4:5]
	s_add_u32 m0, s12, 0x5000
	s_add_u32 s4, s2, 0x50000
	s_addc_u32 s5, s3, 0
	global_load_lds_dwordx4 v180, s[4:5]
	s_add_u32 m0, s12, 0x6000
	s_add_u32 s4, s2, 0x60000
	s_addc_u32 s5, s3, 0
	global_load_lds_dwordx4 v180, s[4:5]
	s_add_u32 m0, s12, 0x7000
	s_add_u32 s4, s2, 0x70000
	s_addc_u32 s5, s3, 0
	global_load_lds_dwordx4 v180, s[4:5]
	s_add_u32 s2, s2, 0x80
	s_addc_u32 s3, s3, 0
.Lg4_pj_nl:
	s_waitcnt lgkmcnt(1)
	v_mfma_f32_16x16x32_f16 v[0:3], v[132:135], v[242:245], v[0:3]
	v_mfma_f32_16x16x32_f16 v[16:19], v[136:139], v[242:245], v[16:19]
	v_mfma_f32_16x16x32_f16 v[32:35], v[140:143], v[242:245], v[32:35]
	v_mfma_f32_16x16x32_f16 v[48:51], v[144:147], v[242:245], v[48:51]
	v_mfma_f32_16x16x32_f16 v[64:67], v[148:151], v[242:245], v[64:67]
	v_mfma_f32_16x16x32_f16 v[80:83], v[152:155], v[242:245], v[80:83]
	v_mfma_f32_16x16x32_f16 v[96:99], v[156:159], v[242:245], v[96:99]
	v_mfma_f32_16x16x32_f16 v[116:119], v[160:163], v[242:245], v[116:119]
	ds_read_b128 v[242:245], v223 offset:36864
	s_waitcnt lgkmcnt(1)
	v_mfma_f32_16x16x32_f16 v[4:7], v[132:135], v[112:115], v[4:7]
	v_mfma_f32_16x16x32_f16 v[20:23], v[136:139], v[112:115], v[20:23]
	v_mfma_f32_16x16x32_f16 v[36:39], v[140:143], v[112:115], v[36:39]
	v_mfma_f32_16x16x32_f16 v[52:55], v[144:147], v[112:115], v[52:55]
	v_mfma_f32_16x16x32_f16 v[68:71], v[148:151], v[112:115], v[68:71]
	v_mfma_f32_16x16x32_f16 v[84:87], v[152:155], v[112:115], v[84:87]
	v_mfma_f32_16x16x32_f16 v[100:103], v[156:159], v[112:115], v[100:103]
	v_mfma_f32_16x16x32_f16 v[120:123], v[160:163], v[112:115], v[120:123]
	ds_read_b128 v[112:115], v223 offset:38912
	s_waitcnt lgkmcnt(1)
	v_mfma_f32_16x16x32_f16 v[8:11], v[132:135], v[242:245], v[8:11]
	v_mfma_f32_16x16x32_f16 v[24:27], v[136:139], v[242:245], v[24:27]
	v_mfma_f32_16x16x32_f16 v[40:43], v[140:143], v[242:245], v[40:43]
	v_mfma_f32_16x16x32_f16 v[56:59], v[144:147], v[242:245], v[56:59]
	v_mfma_f32_16x16x32_f16 v[72:75], v[148:151], v[242:245], v[72:75]
	v_mfma_f32_16x16x32_f16 v[88:91], v[152:155], v[242:245], v[88:91]
	v_mfma_f32_16x16x32_f16 v[104:107], v[156:159], v[242:245], v[104:107]
	v_mfma_f32_16x16x32_f16 v[124:127], v[160:163], v[242:245], v[124:127]
	ds_read_b128 v[242:245], v233 offset:32768
	s_waitcnt lgkmcnt(1)
	v_mfma_f32_16x16x32_f16 v[12:15], v[132:135], v[112:115], v[12:15]
	v_mfma_f32_16x16x32_f16 v[28:31], v[136:139], v[112:115], v[28:31]
	v_mfma_f32_16x16x32_f16 v[44:47], v[140:143], v[112:115], v[44:47]
	v_mfma_f32_16x16x32_f16 v[60:63], v[144:147], v[112:115], v[60:63]
	v_mfma_f32_16x16x32_f16 v[76:79], v[148:151], v[112:115], v[76:79]
	v_mfma_f32_16x16x32_f16 v[92:95], v[152:155], v[112:115], v[92:95]
	v_mfma_f32_16x16x32_f16 v[108:111], v[156:159], v[112:115], v[108:111]
	v_mfma_f32_16x16x32_f16 v[128:131], v[160:163], v[112:115], v[128:131]
	ds_read_b128 v[112:115], v233 offset:34816
	s_waitcnt lgkmcnt(1)
	v_mfma_f32_16x16x32_f16 v[0:3], v[164:167], v[242:245], v[0:3]
	v_mfma_f32_16x16x32_f16 v[16:19], v[168:171], v[242:245], v[16:19]
	v_mfma_f32_16x16x32_f16 v[32:35], v[172:175], v[242:245], v[32:35]
	v_mfma_f32_16x16x32_f16 v[48:51], v[176:179], v[242:245], v[48:51]
	v_mfma_f32_16x16x32_f16 v[64:67], v[224:227], v[242:245], v[64:67]
	v_mfma_f32_16x16x32_f16 v[80:83], v[228:231], v[242:245], v[80:83]
	v_mfma_f32_16x16x32_f16 v[96:99], v[234:237], v[242:245], v[96:99]
	v_mfma_f32_16x16x32_f16 v[116:119], v[238:241], v[242:245], v[116:119]
	ds_read_b128 v[242:245], v233 offset:36864
	s_waitcnt lgkmcnt(1)
	v_mfma_f32_16x16x32_f16 v[4:7], v[164:167], v[112:115], v[4:7]
	v_mfma_f32_16x16x32_f16 v[20:23], v[168:171], v[112:115], v[20:23]
	v_mfma_f32_16x16x32_f16 v[36:39], v[172:175], v[112:115], v[36:39]
	v_mfma_f32_16x16x32_f16 v[52:55], v[176:179], v[112:115], v[52:55]
	v_mfma_f32_16x16x32_f16 v[68:71], v[224:227], v[112:115], v[68:71]
	v_mfma_f32_16x16x32_f16 v[84:87], v[228:231], v[112:115], v[84:87]
	v_mfma_f32_16x16x32_f16 v[100:103], v[234:237], v[112:115], v[100:103]
	v_mfma_f32_16x16x32_f16 v[120:123], v[238:241], v[112:115], v[120:123]
	ds_read_b128 v[112:115], v233 offset:38912
	s_waitcnt lgkmcnt(1)
	v_mfma_f32_16x16x32_f16 v[8:11], v[164:167], v[242:245], v[8:11]
	v_mfma_f32_16x16x32_f16 v[24:27], v[168:171], v[242:245], v[24:27]
	v_mfma_f32_16x16x32_f16 v[40:43], v[172:175], v[242:245], v[40:43]
	v_mfma_f32_16x16x32_f16 v[56:59], v[176:179], v[242:245], v[56:59]
	v_mfma_f32_16x16x32_f16 v[72:75], v[224:227], v[242:245], v[72:75]
	v_mfma_f32_16x16x32_f16 v[88:91], v[228:231], v[242:245], v[88:91]
	v_mfma_f32_16x16x32_f16 v[104:107], v[234:237], v[242:245], v[104:107]
	v_mfma_f32_16x16x32_f16 v[124:127], v[238:241], v[242:245], v[124:127]
	s_waitcnt lgkmcnt(0)
	v_mfma_f32_16x16x32_f16 v[12:15], v[164:167], v[112:115], v[12:15]
	v_mfma_f32_16x16x32_f16 v[28:31], v[168:171], v[112:115], v[28:31]
	v_mfma_f32_16x16x32_f16 v[44:47], v[172:175], v[112:115], v[44:47]
	v_mfma_f32_16x16x32_f16 v[60:63], v[176:179], v[112:115], v[60:63]
	v_mfma_f32_16x16x32_f16 v[76:79], v[224:227], v[112:115], v[76:79]
	v_mfma_f32_16x16x32_f16 v[92:95], v[228:231], v[112:115], v[92:95]
	v_mfma_f32_16x16x32_f16 v[108:111], v[234:237], v[112:115], v[108:111]
	v_mfma_f32_16x16x32_f16 v[128:131], v[238:241], v[112:115], v[128:131]
	v_xor_b32_e32 v223, 0x4000, v223
	v_xor_b32_e32 v233, 0x4000, v233
	s_sub_u32 s15, s15, 1
	s_cmp_lg_u32 s15, -1
	s_cbranch_scc1 .Lg4_pj
	s_nop 7
	v_bfe_u32 v132, v182, 7, 1
	v_bfe_u32 v133, v182, 4, 2
	v_bfe_u32 v134, v182, 6, 1
	v_and_b32_e32 v135, 15, v182
	s_cmp_eq_u32 s22, 30
	s_cbranch_scc1 .Lg4_pj_gates
	s_sub_u32 s13, s22, 15
	s_cmp_lt_u32 s13, 3
	s_cbranch_scc1 .Lg4_pj_vc
	s_sub_u32 s13, s22, 20
	s_cmp_lt_u32 s13, 2
	s_cbranch_scc1 .Lg4_pj_vb
	s_cmp_lt_u32 s22, 15
	s_cselect_b32 s13, 0, 0x180
	s_cmp_lt_u32 s22, 20
	s_cselect_b32 s13, s13, 0x280
	s_sub_u32 s13, s23, s13
	s_lshl_b32 s13, s13, 1
	s_mul_i32 s14, s0, 0x1900
	s_add_u32 s13, s13, s14
	s_add_u32 s98, s30, s13
	s_addc_u32 s99, s31, 0
	v_lshlrev_b32_e32 v136, 2, v133
	v_lshl_or_b32 v136, v132, 7, v136
	v_mul_u32_u24_e32 v136, 0x1900, v136
	v_lshl_or_b32 v132, v134, 6, v135
	v_lshl_add_u32 v136, v132, 1, v136
	s_mov_b64 s[100:101], s[98:99]
	v_med3_f32 v138, v0, s57, v194
	v_med3_f32 v139, v4, s57, v194
	v_med3_f32 v140, v8, s57, v194
	v_med3_f32 v141, v12, s57, v194
	v_cvt_f16_f32_e32 v138, v138
	v_cvt_f16_f32_e32 v139, v139
	v_cvt_f16_f32_e32 v140, v140
	v_cvt_f16_f32_e32 v141, v141
	global_store_short v136, v138, s[100:101]
	global_store_short v136, v139, s[100:101] offset:32
	global_store_short v136, v140, s[100:101] offset:64
	global_store_short v136, v141, s[100:101] offset:96
	s_add_u32 s100, s98, 0x1900
	s_addc_u32 s101, s99, 0
	v_med3_f32 v138, v1, s57, v194
	v_med3_f32 v139, v5, s57, v194
	v_med3_f32 v140, v9, s57, v194
	v_med3_f32 v141, v13, s57, v194
	v_cvt_f16_f32_e32 v138, v138
	v_cvt_f16_f32_e32 v139, v139
	v_cvt_f16_f32_e32 v140, v140
	v_cvt_f16_f32_e32 v141, v141
	global_store_short v136, v138, s[100:101]
	global_store_short v136, v139, s[100:101] offset:32
	global_store_short v136, v140, s[100:101] offset:64
	global_store_short v136, v141, s[100:101] offset:96
	s_add_u32 s100, s98, 0x3200
	s_addc_u32 s101, s99, 0
	v_med3_f32 v138, v2, s57, v194
	v_med3_f32 v139, v6, s57, v194
	v_med3_f32 v140, v10, s57, v194
	v_med3_f32 v141, v14, s57, v194
	v_cvt_f16_f32_e32 v138, v138
	v_cvt_f16_f32_e32 v139, v139
	v_cvt_f16_f32_e32 v140, v140
	v_cvt_f16_f32_e32 v141, v141
	global_store_short v136, v138, s[100:101]
	global_store_short v136, v139, s[100:101] offset:32
	global_store_short v136, v140, s[100:101] offset:64
	global_store_short v136, v141, s[100:101] offset:96
	s_add_u32 s100, s98, 0x4b00
	s_addc_u32 s101, s99, 0
	v_med3_f32 v138, v3, s57, v194
	v_med3_f32 v139, v7, s57, v194
	v_med3_f32 v140, v11, s57, v194
	v_med3_f32 v141, v15, s57, v194
	v_cvt_f16_f32_e32 v138, v138
	v_cvt_f16_f32_e32 v139, v139
	v_cvt_f16_f32_e32 v140, v140
	v_cvt_f16_f32_e32 v141, v141
	global_store_short v136, v138, s[100:101]
	global_store_short v136, v139, s[100:101] offset:32
	global_store_short v136, v140, s[100:101] offset:64
	global_store_short v136, v141, s[100:101] offset:96
	s_add_u32 s100, s98, 0x19000
	s_addc_u32 s101, s99, 0
	v_med3_f32 v138, v16, s57, v194
	v_med3_f32 v139, v20, s57, v194
	v_med3_f32 v140, v24, s57, v194
	v_med3_f32 v141, v28, s57, v194
	v_cvt_f16_f32_e32 v138, v138
	v_cvt_f16_f32_e32 v139, v139
	v_cvt_f16_f32_e32 v140, v140
	v_cvt_f16_f32_e32 v141, v141
	global_store_short v136, v138, s[100:101]
	global_store_short v136, v139, s[100:101] offset:32
	global_store_short v136, v140, s[100:101] offset:64
	global_store_short v136, v141, s[100:101] offset:96
	s_add_u32 s100, s98, 0x1a900
	s_addc_u32 s101, s99, 0
	v_med3_f32 v138, v17, s57, v194
	v_med3_f32 v139, v21, s57, v194
	v_med3_f32 v140, v25, s57, v194
	v_med3_f32 v141, v29, s57, v194
	v_cvt_f16_f32_e32 v138, v138
	v_cvt_f16_f32_e32 v139, v139
	v_cvt_f16_f32_e32 v140, v140
	v_cvt_f16_f32_e32 v141, v141
	global_store_short v136, v138, s[100:101]
	global_store_short v136, v139, s[100:101] offset:32
	global_store_short v136, v140, s[100:101] offset:64
	global_store_short v136, v141, s[100:101] offset:96
	s_add_u32 s100, s98, 0x1c200
	s_addc_u32 s101, s99, 0
	v_med3_f32 v138, v18, s57, v194
	v_med3_f32 v139, v22, s57, v194
	v_med3_f32 v140, v26, s57, v194
	v_med3_f32 v141, v30, s57, v194
	v_cvt_f16_f32_e32 v138, v138
	v_cvt_f16_f32_e32 v139, v139
	v_cvt_f16_f32_e32 v140, v140
	v_cvt_f16_f32_e32 v141, v141
	global_store_short v136, v138, s[100:101]
	global_store_short v136, v139, s[100:101] offset:32
	global_store_short v136, v140, s[100:101] offset:64
	global_store_short v136, v141, s[100:101] offset:96
	s_add_u32 s100, s98, 0x1db00
	s_addc_u32 s101, s99, 0
	v_med3_f32 v138, v19, s57, v194
	v_med3_f32 v139, v23, s57, v194
	v_med3_f32 v140, v27, s57, v194
	v_med3_f32 v141, v31, s57, v194
	v_cvt_f16_f32_e32 v138, v138
	v_cvt_f16_f32_e32 v139, v139
	v_cvt_f16_f32_e32 v140, v140
	v_cvt_f16_f32_e32 v141, v141
	global_store_short v136, v138, s[100:101]
	global_store_short v136, v139, s[100:101] offset:32
	global_store_short v136, v140, s[100:101] offset:64
	global_store_short v136, v141, s[100:101] offset:96
	s_add_u32 s100, s98, 0x32000
	s_addc_u32 s101, s99, 0
	v_med3_f32 v138, v32, s57, v194
	v_med3_f32 v139, v36, s57, v194
	v_med3_f32 v140, v40, s57, v194
	v_med3_f32 v141, v44, s57, v194
	v_cvt_f16_f32_e32 v138, v138
	v_cvt_f16_f32_e32 v139, v139
	v_cvt_f16_f32_e32 v140, v140
	v_cvt_f16_f32_e32 v141, v141
	global_store_short v136, v138, s[100:101]
	global_store_short v136, v139, s[100:101] offset:32
	global_store_short v136, v140, s[100:101] offset:64
	global_store_short v136, v141, s[100:101] offset:96
	s_add_u32 s100, s98, 0x33900
	s_addc_u32 s101, s99, 0
	v_med3_f32 v138, v33, s57, v194
	v_med3_f32 v139, v37, s57, v194
	v_med3_f32 v140, v41, s57, v194
	v_med3_f32 v141, v45, s57, v194
	v_cvt_f16_f32_e32 v138, v138
	v_cvt_f16_f32_e32 v139, v139
	v_cvt_f16_f32_e32 v140, v140
	v_cvt_f16_f32_e32 v141, v141
	global_store_short v136, v138, s[100:101]
	global_store_short v136, v139, s[100:101] offset:32
	global_store_short v136, v140, s[100:101] offset:64
	global_store_short v136, v141, s[100:101] offset:96
	s_add_u32 s100, s98, 0x35200
	s_addc_u32 s101, s99, 0
	v_med3_f32 v138, v34, s57, v194
	v_med3_f32 v139, v38, s57, v194
	v_med3_f32 v140, v42, s57, v194
	v_med3_f32 v141, v46, s57, v194
	v_cvt_f16_f32_e32 v138, v138
	v_cvt_f16_f32_e32 v139, v139
	v_cvt_f16_f32_e32 v140, v140
	v_cvt_f16_f32_e32 v141, v141
	global_store_short v136, v138, s[100:101]
	global_store_short v136, v139, s[100:101] offset:32
	global_store_short v136, v140, s[100:101] offset:64
	global_store_short v136, v141, s[100:101] offset:96
	s_add_u32 s100, s98, 0x36b00
	s_addc_u32 s101, s99, 0
	v_med3_f32 v138, v35, s57, v194
	v_med3_f32 v139, v39, s57, v194
	v_med3_f32 v140, v43, s57, v194
	v_med3_f32 v141, v47, s57, v194
	v_cvt_f16_f32_e32 v138, v138
	v_cvt_f16_f32_e32 v139, v139
	v_cvt_f16_f32_e32 v140, v140
	v_cvt_f16_f32_e32 v141, v141
	global_store_short v136, v138, s[100:101]
	global_store_short v136, v139, s[100:101] offset:32
	global_store_short v136, v140, s[100:101] offset:64
	global_store_short v136, v141, s[100:101] offset:96
	s_add_u32 s100, s98, 0x4b000
	s_addc_u32 s101, s99, 0
	v_med3_f32 v138, v48, s57, v194
	v_med3_f32 v139, v52, s57, v194
	v_med3_f32 v140, v56, s57, v194
	v_med3_f32 v141, v60, s57, v194
	v_cvt_f16_f32_e32 v138, v138
	v_cvt_f16_f32_e32 v139, v139
	v_cvt_f16_f32_e32 v140, v140
	v_cvt_f16_f32_e32 v141, v141
	global_store_short v136, v138, s[100:101]
	global_store_short v136, v139, s[100:101] offset:32
	global_store_short v136, v140, s[100:101] offset:64
	global_store_short v136, v141, s[100:101] offset:96
	s_add_u32 s100, s98, 0x4c900
	s_addc_u32 s101, s99, 0
	v_med3_f32 v138, v49, s57, v194
	v_med3_f32 v139, v53, s57, v194
	v_med3_f32 v140, v57, s57, v194
	v_med3_f32 v141, v61, s57, v194
	v_cvt_f16_f32_e32 v138, v138
	v_cvt_f16_f32_e32 v139, v139
	v_cvt_f16_f32_e32 v140, v140
	v_cvt_f16_f32_e32 v141, v141
	global_store_short v136, v138, s[100:101]
	global_store_short v136, v139, s[100:101] offset:32
	global_store_short v136, v140, s[100:101] offset:64
	global_store_short v136, v141, s[100:101] offset:96
	s_add_u32 s100, s98, 0x4e200
	s_addc_u32 s101, s99, 0
	v_med3_f32 v138, v50, s57, v194
	v_med3_f32 v139, v54, s57, v194
	v_med3_f32 v140, v58, s57, v194
	v_med3_f32 v141, v62, s57, v194
	v_cvt_f16_f32_e32 v138, v138
	v_cvt_f16_f32_e32 v139, v139
	v_cvt_f16_f32_e32 v140, v140
	v_cvt_f16_f32_e32 v141, v141
	global_store_short v136, v138, s[100:101]
	global_store_short v136, v139, s[100:101] offset:32
	global_store_short v136, v140, s[100:101] offset:64
	global_store_short v136, v141, s[100:101] offset:96
	s_add_u32 s100, s98, 0x4fb00
	s_addc_u32 s101, s99, 0
	v_med3_f32 v138, v51, s57, v194
	v_med3_f32 v139, v55, s57, v194
	v_med3_f32 v140, v59, s57, v194
	v_med3_f32 v141, v63, s57, v194
	v_cvt_f16_f32_e32 v138, v138
	v_cvt_f16_f32_e32 v139, v139
	v_cvt_f16_f32_e32 v140, v140
	v_cvt_f16_f32_e32 v141, v141
	global_store_short v136, v138, s[100:101]
	global_store_short v136, v139, s[100:101] offset:32
	global_store_short v136, v140, s[100:101] offset:64
	global_store_short v136, v141, s[100:101] offset:96
	s_add_u32 s100, s98, 0x64000
	s_addc_u32 s101, s99, 0
	v_med3_f32 v138, v64, s57, v194
	v_med3_f32 v139, v68, s57, v194
	v_med3_f32 v140, v72, s57, v194
	v_med3_f32 v141, v76, s57, v194
	v_cvt_f16_f32_e32 v138, v138
	v_cvt_f16_f32_e32 v139, v139
	v_cvt_f16_f32_e32 v140, v140
	v_cvt_f16_f32_e32 v141, v141
	global_store_short v136, v138, s[100:101]
	global_store_short v136, v139, s[100:101] offset:32
	global_store_short v136, v140, s[100:101] offset:64
	global_store_short v136, v141, s[100:101] offset:96
	s_add_u32 s100, s98, 0x65900
	s_addc_u32 s101, s99, 0
	v_med3_f32 v138, v65, s57, v194
	v_med3_f32 v139, v69, s57, v194
	v_med3_f32 v140, v73, s57, v194
	v_med3_f32 v141, v77, s57, v194
	v_cvt_f16_f32_e32 v138, v138
	v_cvt_f16_f32_e32 v139, v139
	v_cvt_f16_f32_e32 v140, v140
	v_cvt_f16_f32_e32 v141, v141
	global_store_short v136, v138, s[100:101]
	global_store_short v136, v139, s[100:101] offset:32
	global_store_short v136, v140, s[100:101] offset:64
	global_store_short v136, v141, s[100:101] offset:96
	s_add_u32 s100, s98, 0x67200
	s_addc_u32 s101, s99, 0
	v_med3_f32 v138, v66, s57, v194
	v_med3_f32 v139, v70, s57, v194
	v_med3_f32 v140, v74, s57, v194
	v_med3_f32 v141, v78, s57, v194
	v_cvt_f16_f32_e32 v138, v138
	v_cvt_f16_f32_e32 v139, v139
	v_cvt_f16_f32_e32 v140, v140
	v_cvt_f16_f32_e32 v141, v141
	global_store_short v136, v138, s[100:101]
	global_store_short v136, v139, s[100:101] offset:32
	global_store_short v136, v140, s[100:101] offset:64
	global_store_short v136, v141, s[100:101] offset:96
	s_add_u32 s100, s98, 0x68b00
	s_addc_u32 s101, s99, 0
	v_med3_f32 v138, v67, s57, v194
	v_med3_f32 v139, v71, s57, v194
	v_med3_f32 v140, v75, s57, v194
	v_med3_f32 v141, v79, s57, v194
	v_cvt_f16_f32_e32 v138, v138
	v_cvt_f16_f32_e32 v139, v139
	v_cvt_f16_f32_e32 v140, v140
	v_cvt_f16_f32_e32 v141, v141
	global_store_short v136, v138, s[100:101]
	global_store_short v136, v139, s[100:101] offset:32
	global_store_short v136, v140, s[100:101] offset:64
	global_store_short v136, v141, s[100:101] offset:96
	s_add_u32 s100, s98, 0x7d000
	s_addc_u32 s101, s99, 0
	v_med3_f32 v138, v80, s57, v194
	v_med3_f32 v139, v84, s57, v194
	v_med3_f32 v140, v88, s57, v194
	v_med3_f32 v141, v92, s57, v194
	v_cvt_f16_f32_e32 v138, v138
	v_cvt_f16_f32_e32 v139, v139
	v_cvt_f16_f32_e32 v140, v140
	v_cvt_f16_f32_e32 v141, v141
	global_store_short v136, v138, s[100:101]
	global_store_short v136, v139, s[100:101] offset:32
	global_store_short v136, v140, s[100:101] offset:64
	global_store_short v136, v141, s[100:101] offset:96
	s_add_u32 s100, s98, 0x7e900
	s_addc_u32 s101, s99, 0
	v_med3_f32 v138, v81, s57, v194
	v_med3_f32 v139, v85, s57, v194
	v_med3_f32 v140, v89, s57, v194
	v_med3_f32 v141, v93, s57, v194
	v_cvt_f16_f32_e32 v138, v138
	v_cvt_f16_f32_e32 v139, v139
	v_cvt_f16_f32_e32 v140, v140
	v_cvt_f16_f32_e32 v141, v141
	global_store_short v136, v138, s[100:101]
	global_store_short v136, v139, s[100:101] offset:32
	global_store_short v136, v140, s[100:101] offset:64
	global_store_short v136, v141, s[100:101] offset:96
	s_add_u32 s100, s98, 0x80200
	s_addc_u32 s101, s99, 0
	v_med3_f32 v138, v82, s57, v194
	v_med3_f32 v139, v86, s57, v194
	v_med3_f32 v140, v90, s57, v194
	v_med3_f32 v141, v94, s57, v194
	v_cvt_f16_f32_e32 v138, v138
	v_cvt_f16_f32_e32 v139, v139
	v_cvt_f16_f32_e32 v140, v140
	v_cvt_f16_f32_e32 v141, v141
	global_store_short v136, v138, s[100:101]
	global_store_short v136, v139, s[100:101] offset:32
	global_store_short v136, v140, s[100:101] offset:64
	global_store_short v136, v141, s[100:101] offset:96
	s_add_u32 s100, s98, 0x81b00
	s_addc_u32 s101, s99, 0
	v_med3_f32 v138, v83, s57, v194
	v_med3_f32 v139, v87, s57, v194
	v_med3_f32 v140, v91, s57, v194
	v_med3_f32 v141, v95, s57, v194
	v_cvt_f16_f32_e32 v138, v138
	v_cvt_f16_f32_e32 v139, v139
	v_cvt_f16_f32_e32 v140, v140
	v_cvt_f16_f32_e32 v141, v141
	global_store_short v136, v138, s[100:101]
	global_store_short v136, v139, s[100:101] offset:32
	global_store_short v136, v140, s[100:101] offset:64
	global_store_short v136, v141, s[100:101] offset:96
	s_add_u32 s100, s98, 0x96000
	s_addc_u32 s101, s99, 0
	v_med3_f32 v138, v96, s57, v194
	v_med3_f32 v139, v100, s57, v194
	v_med3_f32 v140, v104, s57, v194
	v_med3_f32 v141, v108, s57, v194
	v_cvt_f16_f32_e32 v138, v138
	v_cvt_f16_f32_e32 v139, v139
	v_cvt_f16_f32_e32 v140, v140
	v_cvt_f16_f32_e32 v141, v141
	global_store_short v136, v138, s[100:101]
	global_store_short v136, v139, s[100:101] offset:32
	global_store_short v136, v140, s[100:101] offset:64
	global_store_short v136, v141, s[100:101] offset:96
	s_add_u32 s100, s98, 0x97900
	s_addc_u32 s101, s99, 0
	v_med3_f32 v138, v97, s57, v194
	v_med3_f32 v139, v101, s57, v194
	v_med3_f32 v140, v105, s57, v194
	v_med3_f32 v141, v109, s57, v194
	v_cvt_f16_f32_e32 v138, v138
	v_cvt_f16_f32_e32 v139, v139
	v_cvt_f16_f32_e32 v140, v140
	v_cvt_f16_f32_e32 v141, v141
	global_store_short v136, v138, s[100:101]
	global_store_short v136, v139, s[100:101] offset:32
	global_store_short v136, v140, s[100:101] offset:64
	global_store_short v136, v141, s[100:101] offset:96
	s_add_u32 s100, s98, 0x99200
	s_addc_u32 s101, s99, 0
	v_med3_f32 v138, v98, s57, v194
	v_med3_f32 v139, v102, s57, v194
	v_med3_f32 v140, v106, s57, v194
	v_med3_f32 v141, v110, s57, v194
	v_cvt_f16_f32_e32 v138, v138
	v_cvt_f16_f32_e32 v139, v139
	v_cvt_f16_f32_e32 v140, v140
	v_cvt_f16_f32_e32 v141, v141
	global_store_short v136, v138, s[100:101]
	global_store_short v136, v139, s[100:101] offset:32
	global_store_short v136, v140, s[100:101] offset:64
	global_store_short v136, v141, s[100:101] offset:96
	s_add_u32 s100, s98, 0x9ab00
	s_addc_u32 s101, s99, 0
	v_med3_f32 v138, v99, s57, v194
	v_med3_f32 v139, v103, s57, v194
	v_med3_f32 v140, v107, s57, v194
	v_med3_f32 v141, v111, s57, v194
	v_cvt_f16_f32_e32 v138, v138
	v_cvt_f16_f32_e32 v139, v139
	v_cvt_f16_f32_e32 v140, v140
	v_cvt_f16_f32_e32 v141, v141
	global_store_short v136, v138, s[100:101]
	global_store_short v136, v139, s[100:101] offset:32
	global_store_short v136, v140, s[100:101] offset:64
	global_store_short v136, v141, s[100:101] offset:96
	s_add_u32 s100, s98, 0xaf000
	s_addc_u32 s101, s99, 0
	v_med3_f32 v138, v116, s57, v194
	v_med3_f32 v139, v120, s57, v194
	v_med3_f32 v140, v124, s57, v194
	v_med3_f32 v141, v128, s57, v194
	v_cvt_f16_f32_e32 v138, v138
	v_cvt_f16_f32_e32 v139, v139
	v_cvt_f16_f32_e32 v140, v140
	v_cvt_f16_f32_e32 v141, v141
	global_store_short v136, v138, s[100:101]
	global_store_short v136, v139, s[100:101] offset:32
	global_store_short v136, v140, s[100:101] offset:64
	global_store_short v136, v141, s[100:101] offset:96
	s_add_u32 s100, s98, 0xb0900
	s_addc_u32 s101, s99, 0
	v_med3_f32 v138, v117, s57, v194
	v_med3_f32 v139, v121, s57, v194
	v_med3_f32 v140, v125, s57, v194
	v_med3_f32 v141, v129, s57, v194
	v_cvt_f16_f32_e32 v138, v138
	v_cvt_f16_f32_e32 v139, v139
	v_cvt_f16_f32_e32 v140, v140
	v_cvt_f16_f32_e32 v141, v141
	global_store_short v136, v138, s[100:101]
	global_store_short v136, v139, s[100:101] offset:32
	global_store_short v136, v140, s[100:101] offset:64
	global_store_short v136, v141, s[100:101] offset:96
	s_add_u32 s100, s98, 0xb2200
	s_addc_u32 s101, s99, 0
	v_med3_f32 v138, v118, s57, v194
	v_med3_f32 v139, v122, s57, v194
	v_med3_f32 v140, v126, s57, v194
	v_med3_f32 v141, v130, s57, v194
	v_cvt_f16_f32_e32 v138, v138
	v_cvt_f16_f32_e32 v139, v139
	v_cvt_f16_f32_e32 v140, v140
	v_cvt_f16_f32_e32 v141, v141
	global_store_short v136, v138, s[100:101]
	global_store_short v136, v139, s[100:101] offset:32
	global_store_short v136, v140, s[100:101] offset:64
	global_store_short v136, v141, s[100:101] offset:96
	s_add_u32 s100, s98, 0xb3b00
	s_addc_u32 s101, s99, 0
	v_med3_f32 v138, v119, s57, v194
	v_med3_f32 v139, v123, s57, v194
	v_med3_f32 v140, v127, s57, v194
	v_med3_f32 v141, v131, s57, v194
	v_cvt_f16_f32_e32 v138, v138
	v_cvt_f16_f32_e32 v139, v139
	v_cvt_f16_f32_e32 v140, v140
	v_cvt_f16_f32_e32 v141, v141
	global_store_short v136, v138, s[100:101]
	global_store_short v136, v139, s[100:101] offset:32
	global_store_short v136, v140, s[100:101] offset:64
	global_store_short v136, v141, s[100:101] offset:96
	s_branch .Lg4_pj_done
.Lg4_pj_vc:
	s_lshr_b32 s13, s0, 13
	s_mul_i32 s13, s13, 6
	s_sub_u32 s14, s22, 15
	s_lshl_b32 s14, s14, 1
	s_add_u32 s13, s13, s14
	s_lshl_b32 s13, s13, 20
	s_and_b32 s14, s0, 0x1fff
	s_lshl_b32 s14, s14, 1
	s_add_u32 s13, s13, s14
	s_add_u32 s13, s13, 0x1b700000
	s_add_u32 s98, s30, s13
	s_addc_u32 s99, s31, 0
	v_lshlrev_b32_e32 v136, 20, v134
	v_lshl_add_u32 v136, v135, 14, v136
	v_lshl_add_u32 v136, v132, 8, v136
	v_lshl_add_u32 v136, v133, 3, v136
	s_mov_b64 s[100:101], s[98:99]
	v_med3_f32 v138, v0, s57, v194
	v_med3_f32 v139, v1, s57, v194
	v_med3_f32 v140, v2, s57, v194
	v_med3_f32 v141, v3, s57, v194
	v_cvt_pk_f16_f32 v142, v138, v139
	v_cvt_pk_f16_f32 v143, v140, v141
	global_store_dwordx2 v136, v[142:143], s[100:101]
	v_med3_f32 v138, v16, s57, v194
	v_med3_f32 v139, v17, s57, v194
	v_med3_f32 v140, v18, s57, v194
	v_med3_f32 v141, v19, s57, v194
	v_cvt_pk_f16_f32 v142, v138, v139
	v_cvt_pk_f16_f32 v143, v140, v141
	global_store_dwordx2 v136, v[142:143], s[100:101] offset:32
	v_med3_f32 v138, v32, s57, v194
	v_med3_f32 v139, v33, s57, v194
	v_med3_f32 v140, v34, s57, v194
	v_med3_f32 v141, v35, s57, v194
	v_cvt_pk_f16_f32 v142, v138, v139
	v_cvt_pk_f16_f32 v143, v140, v141
	global_store_dwordx2 v136, v[142:143], s[100:101] offset:64
	v_med3_f32 v138, v48, s57, v194
	v_med3_f32 v139, v49, s57, v194
	v_med3_f32 v140, v50, s57, v194
	v_med3_f32 v141, v51, s57, v194
	v_cvt_pk_f16_f32 v142, v138, v139
	v_cvt_pk_f16_f32 v143, v140, v141
	global_store_dwordx2 v136, v[142:143], s[100:101] offset:96
	v_med3_f32 v138, v64, s57, v194
	v_med3_f32 v139, v65, s57, v194
	v_med3_f32 v140, v66, s57, v194
	v_med3_f32 v141, v67, s57, v194
	v_cvt_pk_f16_f32 v142, v138, v139
	v_cvt_pk_f16_f32 v143, v140, v141
	global_store_dwordx2 v136, v[142:143], s[100:101] offset:128
	v_med3_f32 v138, v80, s57, v194
	v_med3_f32 v139, v81, s57, v194
	v_med3_f32 v140, v82, s57, v194
	v_med3_f32 v141, v83, s57, v194
	v_cvt_pk_f16_f32 v142, v138, v139
	v_cvt_pk_f16_f32 v143, v140, v141
	global_store_dwordx2 v136, v[142:143], s[100:101] offset:160
	v_med3_f32 v138, v96, s57, v194
	v_med3_f32 v139, v97, s57, v194
	v_med3_f32 v140, v98, s57, v194
	v_med3_f32 v141, v99, s57, v194
	v_cvt_pk_f16_f32 v142, v138, v139
	v_cvt_pk_f16_f32 v143, v140, v141
	global_store_dwordx2 v136, v[142:143], s[100:101] offset:192
	v_med3_f32 v138, v116, s57, v194
	v_med3_f32 v139, v117, s57, v194
	v_med3_f32 v140, v118, s57, v194
	v_med3_f32 v141, v119, s57, v194
	v_cvt_pk_f16_f32 v142, v138, v139
	v_cvt_pk_f16_f32 v143, v140, v141
	global_store_dwordx2 v136, v[142:143], s[100:101] offset:224
	s_add_u32 s100, s98, 0x40000
	s_addc_u32 s101, s99, 0
	v_med3_f32 v138, v4, s57, v194
	v_med3_f32 v139, v5, s57, v194
	v_med3_f32 v140, v6, s57, v194
	v_med3_f32 v141, v7, s57, v194
	v_cvt_pk_f16_f32 v142, v138, v139
	v_cvt_pk_f16_f32 v143, v140, v141
	global_store_dwordx2 v136, v[142:143], s[100:101]
	v_med3_f32 v138, v20, s57, v194
	v_med3_f32 v139, v21, s57, v194
	v_med3_f32 v140, v22, s57, v194
	v_med3_f32 v141, v23, s57, v194
	v_cvt_pk_f16_f32 v142, v138, v139
	v_cvt_pk_f16_f32 v143, v140, v141
	global_store_dwordx2 v136, v[142:143], s[100:101] offset:32
	v_med3_f32 v138, v36, s57, v194
	v_med3_f32 v139, v37, s57, v194
	v_med3_f32 v140, v38, s57, v194
	v_med3_f32 v141, v39, s57, v194
	v_cvt_pk_f16_f32 v142, v138, v139
	v_cvt_pk_f16_f32 v143, v140, v141
	global_store_dwordx2 v136, v[142:143], s[100:101] offset:64
	v_med3_f32 v138, v52, s57, v194
	v_med3_f32 v139, v53, s57, v194
	v_med3_f32 v140, v54, s57, v194
	v_med3_f32 v141, v55, s57, v194
	v_cvt_pk_f16_f32 v142, v138, v139
	v_cvt_pk_f16_f32 v143, v140, v141
	global_store_dwordx2 v136, v[142:143], s[100:101] offset:96
	v_med3_f32 v138, v68, s57, v194
	v_med3_f32 v139, v69, s57, v194
	v_med3_f32 v140, v70, s57, v194
	v_med3_f32 v141, v71, s57, v194
	v_cvt_pk_f16_f32 v142, v138, v139
	v_cvt_pk_f16_f32 v143, v140, v141
	global_store_dwordx2 v136, v[142:143], s[100:101] offset:128
	v_med3_f32 v138, v84, s57, v194
	v_med3_f32 v139, v85, s57, v194
	v_med3_f32 v140, v86, s57, v194
	v_med3_f32 v141, v87, s57, v194
	v_cvt_pk_f16_f32 v142, v138, v139
	v_cvt_pk_f16_f32 v143, v140, v141
	global_store_dwordx2 v136, v[142:143], s[100:101] offset:160
	v_med3_f32 v138, v100, s57, v194
	v_med3_f32 v139, v101, s57, v194
	v_med3_f32 v140, v102, s57, v194
	v_med3_f32 v141, v103, s57, v194
	v_cvt_pk_f16_f32 v142, v138, v139
	v_cvt_pk_f16_f32 v143, v140, v141
	global_store_dwordx2 v136, v[142:143], s[100:101] offset:192
	v_med3_f32 v138, v120, s57, v194
	v_med3_f32 v139, v121, s57, v194
	v_med3_f32 v140, v122, s57, v194
	v_med3_f32 v141, v123, s57, v194
	v_cvt_pk_f16_f32 v142, v138, v139
	v_cvt_pk_f16_f32 v143, v140, v141
	global_store_dwordx2 v136, v[142:143], s[100:101] offset:224
	s_add_u32 s100, s98, 0x80000
	s_addc_u32 s101, s99, 0
	v_med3_f32 v138, v8, s57, v194
	v_med3_f32 v139, v9, s57, v194
	v_med3_f32 v140, v10, s57, v194
	v_med3_f32 v141, v11, s57, v194
	v_cvt_pk_f16_f32 v142, v138, v139
	v_cvt_pk_f16_f32 v143, v140, v141
	global_store_dwordx2 v136, v[142:143], s[100:101]
	v_med3_f32 v138, v24, s57, v194
	v_med3_f32 v139, v25, s57, v194
	v_med3_f32 v140, v26, s57, v194
	v_med3_f32 v141, v27, s57, v194
	v_cvt_pk_f16_f32 v142, v138, v139
	v_cvt_pk_f16_f32 v143, v140, v141
	global_store_dwordx2 v136, v[142:143], s[100:101] offset:32
	v_med3_f32 v138, v40, s57, v194
	v_med3_f32 v139, v41, s57, v194
	v_med3_f32 v140, v42, s57, v194
	v_med3_f32 v141, v43, s57, v194
	v_cvt_pk_f16_f32 v142, v138, v139
	v_cvt_pk_f16_f32 v143, v140, v141
	global_store_dwordx2 v136, v[142:143], s[100:101] offset:64
	v_med3_f32 v138, v56, s57, v194
	v_med3_f32 v139, v57, s57, v194
	v_med3_f32 v140, v58, s57, v194
	v_med3_f32 v141, v59, s57, v194
	v_cvt_pk_f16_f32 v142, v138, v139
	v_cvt_pk_f16_f32 v143, v140, v141
	global_store_dwordx2 v136, v[142:143], s[100:101] offset:96
	v_med3_f32 v138, v72, s57, v194
	v_med3_f32 v139, v73, s57, v194
	v_med3_f32 v140, v74, s57, v194
	v_med3_f32 v141, v75, s57, v194
	v_cvt_pk_f16_f32 v142, v138, v139
	v_cvt_pk_f16_f32 v143, v140, v141
	global_store_dwordx2 v136, v[142:143], s[100:101] offset:128
	v_med3_f32 v138, v88, s57, v194
	v_med3_f32 v139, v89, s57, v194
	v_med3_f32 v140, v90, s57, v194
	v_med3_f32 v141, v91, s57, v194
	v_cvt_pk_f16_f32 v142, v138, v139
	v_cvt_pk_f16_f32 v143, v140, v141
	global_store_dwordx2 v136, v[142:143], s[100:101] offset:160
	v_med3_f32 v138, v104, s57, v194
	v_med3_f32 v139, v105, s57, v194
	v_med3_f32 v140, v106, s57, v194
	v_med3_f32 v141, v107, s57, v194
	v_cvt_pk_f16_f32 v142, v138, v139
	v_cvt_pk_f16_f32 v143, v140, v141
	global_store_dwordx2 v136, v[142:143], s[100:101] offset:192
	v_med3_f32 v138, v124, s57, v194
	v_med3_f32 v139, v125, s57, v194
	v_med3_f32 v140, v126, s57, v194
	v_med3_f32 v141, v127, s57, v194
	v_cvt_pk_f16_f32 v142, v138, v139
	v_cvt_pk_f16_f32 v143, v140, v141
	global_store_dwordx2 v136, v[142:143], s[100:101] offset:224
	s_add_u32 s100, s98, 0xc0000
	s_addc_u32 s101, s99, 0
	v_med3_f32 v138, v12, s57, v194
	v_med3_f32 v139, v13, s57, v194
	v_med3_f32 v140, v14, s57, v194
	v_med3_f32 v141, v15, s57, v194
	v_cvt_pk_f16_f32 v142, v138, v139
	v_cvt_pk_f16_f32 v143, v140, v141
	global_store_dwordx2 v136, v[142:143], s[100:101]
	v_med3_f32 v138, v28, s57, v194
	v_med3_f32 v139, v29, s57, v194
	v_med3_f32 v140, v30, s57, v194
	v_med3_f32 v141, v31, s57, v194
	v_cvt_pk_f16_f32 v142, v138, v139
	v_cvt_pk_f16_f32 v143, v140, v141
	global_store_dwordx2 v136, v[142:143], s[100:101] offset:32
	v_med3_f32 v138, v44, s57, v194
	v_med3_f32 v139, v45, s57, v194
	v_med3_f32 v140, v46, s57, v194
	v_med3_f32 v141, v47, s57, v194
	v_cvt_pk_f16_f32 v142, v138, v139
	v_cvt_pk_f16_f32 v143, v140, v141
	global_store_dwordx2 v136, v[142:143], s[100:101] offset:64
	v_med3_f32 v138, v60, s57, v194
	v_med3_f32 v139, v61, s57, v194
	v_med3_f32 v140, v62, s57, v194
	v_med3_f32 v141, v63, s57, v194
	v_cvt_pk_f16_f32 v142, v138, v139
	v_cvt_pk_f16_f32 v143, v140, v141
	global_store_dwordx2 v136, v[142:143], s[100:101] offset:96
	v_med3_f32 v138, v76, s57, v194
	v_med3_f32 v139, v77, s57, v194
	v_med3_f32 v140, v78, s57, v194
	v_med3_f32 v141, v79, s57, v194
	v_cvt_pk_f16_f32 v142, v138, v139
	v_cvt_pk_f16_f32 v143, v140, v141
	global_store_dwordx2 v136, v[142:143], s[100:101] offset:128
	v_med3_f32 v138, v92, s57, v194
	v_med3_f32 v139, v93, s57, v194
	v_med3_f32 v140, v94, s57, v194
	v_med3_f32 v141, v95, s57, v194
	v_cvt_pk_f16_f32 v142, v138, v139
	v_cvt_pk_f16_f32 v143, v140, v141
	global_store_dwordx2 v136, v[142:143], s[100:101] offset:160
	v_med3_f32 v138, v108, s57, v194
	v_med3_f32 v139, v109, s57, v194
	v_med3_f32 v140, v110, s57, v194
	v_med3_f32 v141, v111, s57, v194
	v_cvt_pk_f16_f32 v142, v138, v139
	v_cvt_pk_f16_f32 v143, v140, v141
	global_store_dwordx2 v136, v[142:143], s[100:101] offset:192
	v_med3_f32 v138, v128, s57, v194
	v_med3_f32 v139, v129, s57, v194
	v_med3_f32 v140, v130, s57, v194
	v_med3_f32 v141, v131, s57, v194
	v_cvt_pk_f16_f32 v142, v138, v139
	v_cvt_pk_f16_f32 v143, v140, v141
	global_store_dwordx2 v136, v[142:143], s[100:101] offset:224
	s_branch .Lg4_pj_done
.Lg4_pj_vb:
	s_lshr_b32 s13, s0, 13
	s_mul_i32 s13, s13, 4
	s_sub_u32 s14, s22, 20
	s_lshl_b32 s14, s14, 1
	s_add_u32 s13, s13, s14
	s_lshl_b32 s13, s13, 20
	s_and_b32 s14, s0, 0x1fff
	s_lshl_b32 s14, s14, 1
	s_add_u32 s13, s13, s14
	s_add_u32 s13, s13, 0x1cf00000
	s_add_u32 s98, s30, s13
	s_addc_u32 s99, s31, 0
	v_lshlrev_b32_e32 v136, 20, v134
	v_lshl_add_u32 v136, v135, 14, v136
	v_lshl_add_u32 v136, v132, 8, v136
	v_lshl_add_u32 v136, v133, 3, v136
	s_mov_b64 s[100:101], s[98:99]
	v_med3_f32 v138, v0, s57, v194
	v_med3_f32 v139, v1, s57, v194
	v_med3_f32 v140, v2, s57, v194
	v_med3_f32 v141, v3, s57, v194
	v_cvt_pk_f16_f32 v142, v138, v139
	v_cvt_pk_f16_f32 v143, v140, v141
	global_store_dwordx2 v136, v[142:143], s[100:101]
	v_med3_f32 v138, v16, s57, v194
	v_med3_f32 v139, v17, s57, v194
	v_med3_f32 v140, v18, s57, v194
	v_med3_f32 v141, v19, s57, v194
	v_cvt_pk_f16_f32 v142, v138, v139
	v_cvt_pk_f16_f32 v143, v140, v141
	global_store_dwordx2 v136, v[142:143], s[100:101] offset:32
	v_med3_f32 v138, v32, s57, v194
	v_med3_f32 v139, v33, s57, v194
	v_med3_f32 v140, v34, s57, v194
	v_med3_f32 v141, v35, s57, v194
	v_cvt_pk_f16_f32 v142, v138, v139
	v_cvt_pk_f16_f32 v143, v140, v141
	global_store_dwordx2 v136, v[142:143], s[100:101] offset:64
	v_med3_f32 v138, v48, s57, v194
	v_med3_f32 v139, v49, s57, v194
	v_med3_f32 v140, v50, s57, v194
	v_med3_f32 v141, v51, s57, v194
	v_cvt_pk_f16_f32 v142, v138, v139
	v_cvt_pk_f16_f32 v143, v140, v141
	global_store_dwordx2 v136, v[142:143], s[100:101] offset:96
	v_med3_f32 v138, v64, s57, v194
	v_med3_f32 v139, v65, s57, v194
	v_med3_f32 v140, v66, s57, v194
	v_med3_f32 v141, v67, s57, v194
	v_cvt_pk_f16_f32 v142, v138, v139
	v_cvt_pk_f16_f32 v143, v140, v141
	global_store_dwordx2 v136, v[142:143], s[100:101] offset:128
	v_med3_f32 v138, v80, s57, v194
	v_med3_f32 v139, v81, s57, v194
	v_med3_f32 v140, v82, s57, v194
	v_med3_f32 v141, v83, s57, v194
	v_cvt_pk_f16_f32 v142, v138, v139
	v_cvt_pk_f16_f32 v143, v140, v141
	global_store_dwordx2 v136, v[142:143], s[100:101] offset:160
	v_med3_f32 v138, v96, s57, v194
	v_med3_f32 v139, v97, s57, v194
	v_med3_f32 v140, v98, s57, v194
	v_med3_f32 v141, v99, s57, v194
	v_cvt_pk_f16_f32 v142, v138, v139
	v_cvt_pk_f16_f32 v143, v140, v141
	global_store_dwordx2 v136, v[142:143], s[100:101] offset:192
	v_med3_f32 v138, v116, s57, v194
	v_med3_f32 v139, v117, s57, v194
	v_med3_f32 v140, v118, s57, v194
	v_med3_f32 v141, v119, s57, v194
	v_cvt_pk_f16_f32 v142, v138, v139
	v_cvt_pk_f16_f32 v143, v140, v141
	global_store_dwordx2 v136, v[142:143], s[100:101] offset:224
	s_add_u32 s100, s98, 0x40000
	s_addc_u32 s101, s99, 0
	v_med3_f32 v138, v4, s57, v194
	v_med3_f32 v139, v5, s57, v194
	v_med3_f32 v140, v6, s57, v194
	v_med3_f32 v141, v7, s57, v194
	v_cvt_pk_f16_f32 v142, v138, v139
	v_cvt_pk_f16_f32 v143, v140, v141
	global_store_dwordx2 v136, v[142:143], s[100:101]
	v_med3_f32 v138, v20, s57, v194
	v_med3_f32 v139, v21, s57, v194
	v_med3_f32 v140, v22, s57, v194
	v_med3_f32 v141, v23, s57, v194
	v_cvt_pk_f16_f32 v142, v138, v139
	v_cvt_pk_f16_f32 v143, v140, v141
	global_store_dwordx2 v136, v[142:143], s[100:101] offset:32
	v_med3_f32 v138, v36, s57, v194
	v_med3_f32 v139, v37, s57, v194
	v_med3_f32 v140, v38, s57, v194
	v_med3_f32 v141, v39, s57, v194
	v_cvt_pk_f16_f32 v142, v138, v139
	v_cvt_pk_f16_f32 v143, v140, v141
	global_store_dwordx2 v136, v[142:143], s[100:101] offset:64
	v_med3_f32 v138, v52, s57, v194
	v_med3_f32 v139, v53, s57, v194
	v_med3_f32 v140, v54, s57, v194
	v_med3_f32 v141, v55, s57, v194
	v_cvt_pk_f16_f32 v142, v138, v139
	v_cvt_pk_f16_f32 v143, v140, v141
	global_store_dwordx2 v136, v[142:143], s[100:101] offset:96
	v_med3_f32 v138, v68, s57, v194
	v_med3_f32 v139, v69, s57, v194
	v_med3_f32 v140, v70, s57, v194
	v_med3_f32 v141, v71, s57, v194
	v_cvt_pk_f16_f32 v142, v138, v139
	v_cvt_pk_f16_f32 v143, v140, v141
	global_store_dwordx2 v136, v[142:143], s[100:101] offset:128
	v_med3_f32 v138, v84, s57, v194
	v_med3_f32 v139, v85, s57, v194
	v_med3_f32 v140, v86, s57, v194
	v_med3_f32 v141, v87, s57, v194
	v_cvt_pk_f16_f32 v142, v138, v139
	v_cvt_pk_f16_f32 v143, v140, v141
	global_store_dwordx2 v136, v[142:143], s[100:101] offset:160
	v_med3_f32 v138, v100, s57, v194
	v_med3_f32 v139, v101, s57, v194
	v_med3_f32 v140, v102, s57, v194
	v_med3_f32 v141, v103, s57, v194
	v_cvt_pk_f16_f32 v142, v138, v139
	v_cvt_pk_f16_f32 v143, v140, v141
	global_store_dwordx2 v136, v[142:143], s[100:101] offset:192
	v_med3_f32 v138, v120, s57, v194
	v_med3_f32 v139, v121, s57, v194
	v_med3_f32 v140, v122, s57, v194
	v_med3_f32 v141, v123, s57, v194
	v_cvt_pk_f16_f32 v142, v138, v139
	v_cvt_pk_f16_f32 v143, v140, v141
	global_store_dwordx2 v136, v[142:143], s[100:101] offset:224
	s_add_u32 s100, s98, 0x80000
	s_addc_u32 s101, s99, 0
	v_med3_f32 v138, v8, s57, v194
	v_med3_f32 v139, v9, s57, v194
	v_med3_f32 v140, v10, s57, v194
	v_med3_f32 v141, v11, s57, v194
	v_cvt_pk_f16_f32 v142, v138, v139
	v_cvt_pk_f16_f32 v143, v140, v141
	global_store_dwordx2 v136, v[142:143], s[100:101]
	v_med3_f32 v138, v24, s57, v194
	v_med3_f32 v139, v25, s57, v194
	v_med3_f32 v140, v26, s57, v194
	v_med3_f32 v141, v27, s57, v194
	v_cvt_pk_f16_f32 v142, v138, v139
	v_cvt_pk_f16_f32 v143, v140, v141
	global_store_dwordx2 v136, v[142:143], s[100:101] offset:32
	v_med3_f32 v138, v40, s57, v194
	v_med3_f32 v139, v41, s57, v194
	v_med3_f32 v140, v42, s57, v194
	v_med3_f32 v141, v43, s57, v194
	v_cvt_pk_f16_f32 v142, v138, v139
	v_cvt_pk_f16_f32 v143, v140, v141
	global_store_dwordx2 v136, v[142:143], s[100:101] offset:64
	v_med3_f32 v138, v56, s57, v194
	v_med3_f32 v139, v57, s57, v194
	v_med3_f32 v140, v58, s57, v194
	v_med3_f32 v141, v59, s57, v194
	v_cvt_pk_f16_f32 v142, v138, v139
	v_cvt_pk_f16_f32 v143, v140, v141
	global_store_dwordx2 v136, v[142:143], s[100:101] offset:96
	v_med3_f32 v138, v72, s57, v194
	v_med3_f32 v139, v73, s57, v194
	v_med3_f32 v140, v74, s57, v194
	v_med3_f32 v141, v75, s57, v194
	v_cvt_pk_f16_f32 v142, v138, v139
	v_cvt_pk_f16_f32 v143, v140, v141
	global_store_dwordx2 v136, v[142:143], s[100:101] offset:128
	v_med3_f32 v138, v88, s57, v194
	v_med3_f32 v139, v89, s57, v194
	v_med3_f32 v140, v90, s57, v194
	v_med3_f32 v141, v91, s57, v194
	v_cvt_pk_f16_f32 v142, v138, v139
	v_cvt_pk_f16_f32 v143, v140, v141
	global_store_dwordx2 v136, v[142:143], s[100:101] offset:160
	v_med3_f32 v138, v104, s57, v194
	v_med3_f32 v139, v105, s57, v194
	v_med3_f32 v140, v106, s57, v194
	v_med3_f32 v141, v107, s57, v194
	v_cvt_pk_f16_f32 v142, v138, v139
	v_cvt_pk_f16_f32 v143, v140, v141
	global_store_dwordx2 v136, v[142:143], s[100:101] offset:192
	v_med3_f32 v138, v124, s57, v194
	v_med3_f32 v139, v125, s57, v194
	v_med3_f32 v140, v126, s57, v194
	v_med3_f32 v141, v127, s57, v194
	v_cvt_pk_f16_f32 v142, v138, v139
	v_cvt_pk_f16_f32 v143, v140, v141
	global_store_dwordx2 v136, v[142:143], s[100:101] offset:224
	s_add_u32 s100, s98, 0xc0000
	s_addc_u32 s101, s99, 0
	v_med3_f32 v138, v12, s57, v194
	v_med3_f32 v139, v13, s57, v194
	v_med3_f32 v140, v14, s57, v194
	v_med3_f32 v141, v15, s57, v194
	v_cvt_pk_f16_f32 v142, v138, v139
	v_cvt_pk_f16_f32 v143, v140, v141
	global_store_dwordx2 v136, v[142:143], s[100:101]
	v_med3_f32 v138, v28, s57, v194
	v_med3_f32 v139, v29, s57, v194
	v_med3_f32 v140, v30, s57, v194
	v_med3_f32 v141, v31, s57, v194
	v_cvt_pk_f16_f32 v142, v138, v139
	v_cvt_pk_f16_f32 v143, v140, v141
	global_store_dwordx2 v136, v[142:143], s[100:101] offset:32
	v_med3_f32 v138, v44, s57, v194
	v_med3_f32 v139, v45, s57, v194
	v_med3_f32 v140, v46, s57, v194
	v_med3_f32 v141, v47, s57, v194
	v_cvt_pk_f16_f32 v142, v138, v139
	v_cvt_pk_f16_f32 v143, v140, v141
	global_store_dwordx2 v136, v[142:143], s[100:101] offset:64
	v_med3_f32 v138, v60, s57, v194
	v_med3_f32 v139, v61, s57, v194
	v_med3_f32 v140, v62, s57, v194
	v_med3_f32 v141, v63, s57, v194
	v_cvt_pk_f16_f32 v142, v138, v139
	v_cvt_pk_f16_f32 v143, v140, v141
	global_store_dwordx2 v136, v[142:143], s[100:101] offset:96
	v_med3_f32 v138, v76, s57, v194
	v_med3_f32 v139, v77, s57, v194
	v_med3_f32 v140, v78, s57, v194
	v_med3_f32 v141, v79, s57, v194
	v_cvt_pk_f16_f32 v142, v138, v139
	v_cvt_pk_f16_f32 v143, v140, v141
	global_store_dwordx2 v136, v[142:143], s[100:101] offset:128
	v_med3_f32 v138, v92, s57, v194
	v_med3_f32 v139, v93, s57, v194
	v_med3_f32 v140, v94, s57, v194
	v_med3_f32 v141, v95, s57, v194
	v_cvt_pk_f16_f32 v142, v138, v139
	v_cvt_pk_f16_f32 v143, v140, v141
	global_store_dwordx2 v136, v[142:143], s[100:101] offset:160
	v_med3_f32 v138, v108, s57, v194
	v_med3_f32 v139, v109, s57, v194
	v_med3_f32 v140, v110, s57, v194
	v_med3_f32 v141, v111, s57, v194
	v_cvt_pk_f16_f32 v142, v138, v139
	v_cvt_pk_f16_f32 v143, v140, v141
	global_store_dwordx2 v136, v[142:143], s[100:101] offset:192
	v_med3_f32 v138, v128, s57, v194
	v_med3_f32 v139, v129, s57, v194
	v_med3_f32 v140, v130, s57, v194
	v_med3_f32 v141, v131, s57, v194
	v_cvt_pk_f16_f32 v142, v138, v139
	v_cvt_pk_f16_f32 v143, v140, v141
	global_store_dwordx2 v136, v[142:143], s[100:101] offset:224
	s_branch .Lg4_pj_done
.Lg4_pj_gates:
	s_bitcmp1_b32 s12, 10
	s_cbranch_scc1 .Lg4_pj_done
	s_mul_i32 s13, s0, 96
	s_add_u32 s13, s13, 0x1df00000
	s_add_u32 s98, s30, s13
	s_addc_u32 s99, s31, 0
	v_lshlrev_b32_e32 v136, 2, v133
	v_lshl_or_b32 v136, v132, 7, v136
	v_mul_u32_u24_e32 v136, 96, v136
	v_lshl_add_u32 v136, v135, 2, v136
	s_mov_b64 s[100:101], s[98:99]
	global_store_dword v136, v0, s[100:101] offset:0
	global_store_dword v136, v1, s[100:101] offset:96
	global_store_dword v136, v2, s[100:101] offset:192
	global_store_dword v136, v3, s[100:101] offset:288
	s_add_u32 s100, s98, 0x600
	s_addc_u32 s101, s99, 0
	global_store_dword v136, v16, s[100:101] offset:0
	global_store_dword v136, v17, s[100:101] offset:96
	global_store_dword v136, v18, s[100:101] offset:192
	global_store_dword v136, v19, s[100:101] offset:288
	s_add_u32 s100, s98, 0xc00
	s_addc_u32 s101, s99, 0
	global_store_dword v136, v32, s[100:101] offset:0
	global_store_dword v136, v33, s[100:101] offset:96
	global_store_dword v136, v34, s[100:101] offset:192
	global_store_dword v136, v35, s[100:101] offset:288
	s_add_u32 s100, s98, 0x1200
	s_addc_u32 s101, s99, 0
	global_store_dword v136, v48, s[100:101] offset:0
	global_store_dword v136, v49, s[100:101] offset:96
	global_store_dword v136, v50, s[100:101] offset:192
	global_store_dword v136, v51, s[100:101] offset:288
	s_add_u32 s100, s98, 0x1800
	s_addc_u32 s101, s99, 0
	global_store_dword v136, v64, s[100:101] offset:0
	global_store_dword v136, v65, s[100:101] offset:96
	global_store_dword v136, v66, s[100:101] offset:192
	global_store_dword v136, v67, s[100:101] offset:288
	s_add_u32 s100, s98, 0x1e00
	s_addc_u32 s101, s99, 0
	global_store_dword v136, v80, s[100:101] offset:0
	global_store_dword v136, v81, s[100:101] offset:96
	global_store_dword v136, v82, s[100:101] offset:192
	global_store_dword v136, v83, s[100:101] offset:288
	s_add_u32 s100, s98, 0x2400
	s_addc_u32 s101, s99, 0
	global_store_dword v136, v96, s[100:101] offset:0
	global_store_dword v136, v97, s[100:101] offset:96
	global_store_dword v136, v98, s[100:101] offset:192
	global_store_dword v136, v99, s[100:101] offset:288
	s_add_u32 s100, s98, 0x2a00
	s_addc_u32 s101, s99, 0
	global_store_dword v136, v116, s[100:101] offset:0
	global_store_dword v136, v117, s[100:101] offset:96
	global_store_dword v136, v118, s[100:101] offset:192
	global_store_dword v136, v119, s[100:101] offset:288
	s_mov_b32 exec_lo, 0x00ff00ff
	s_mov_b32 exec_hi, 0x00ff00ff
	s_mov_b64 s[100:101], s[98:99]
	global_store_dword v136, v4, s[100:101] offset:64
	global_store_dword v136, v5, s[100:101] offset:160
	global_store_dword v136, v6, s[100:101] offset:256
	global_store_dword v136, v7, s[100:101] offset:352
	s_add_u32 s100, s98, 0x600
	s_addc_u32 s101, s99, 0
	global_store_dword v136, v20, s[100:101] offset:64
	global_store_dword v136, v21, s[100:101] offset:160
	global_store_dword v136, v22, s[100:101] offset:256
	global_store_dword v136, v23, s[100:101] offset:352
	s_add_u32 s100, s98, 0xc00
	s_addc_u32 s101, s99, 0
	global_store_dword v136, v36, s[100:101] offset:64
	global_store_dword v136, v37, s[100:101] offset:160
	global_store_dword v136, v38, s[100:101] offset:256
	global_store_dword v136, v39, s[100:101] offset:352
	s_add_u32 s100, s98, 0x1200
	s_addc_u32 s101, s99, 0
	global_store_dword v136, v52, s[100:101] offset:64
	global_store_dword v136, v53, s[100:101] offset:160
	global_store_dword v136, v54, s[100:101] offset:256
	global_store_dword v136, v55, s[100:101] offset:352
	s_add_u32 s100, s98, 0x1800
	s_addc_u32 s101, s99, 0
	global_store_dword v136, v68, s[100:101] offset:64
	global_store_dword v136, v69, s[100:101] offset:160
	global_store_dword v136, v70, s[100:101] offset:256
	global_store_dword v136, v71, s[100:101] offset:352
	s_add_u32 s100, s98, 0x1e00
	s_addc_u32 s101, s99, 0
	global_store_dword v136, v84, s[100:101] offset:64
	global_store_dword v136, v85, s[100:101] offset:160
	global_store_dword v136, v86, s[100:101] offset:256
	global_store_dword v136, v87, s[100:101] offset:352
	s_add_u32 s100, s98, 0x2400
	s_addc_u32 s101, s99, 0
	global_store_dword v136, v100, s[100:101] offset:64
	global_store_dword v136, v101, s[100:101] offset:160
	global_store_dword v136, v102, s[100:101] offset:256
	global_store_dword v136, v103, s[100:101] offset:352
	s_add_u32 s100, s98, 0x2a00
	s_addc_u32 s101, s99, 0
	global_store_dword v136, v120, s[100:101] offset:64
	global_store_dword v136, v121, s[100:101] offset:160
	global_store_dword v136, v122, s[100:101] offset:256
	global_store_dword v136, v123, s[100:101] offset:352
	s_mov_b64 exec, -1

.LBB0_247:
	v_mov_b32_e32 v113, 0
	v_mov_b32_e32 v114, 0x3f317218
	v_readlane_b32 s0, v250, 37
	v_readlane_b32 s1, v250, 38
	v_mov_b32_e32 v0, v182
	s_andn2_b64 vcc, exec, s[0:1]
	s_cbranch_vccnz .LBB0_253
	v_lshrrev_b32_e32 v1, 4, v0
	v_bfe_u32 v2, v0, 4, 2
	v_and_b32_e32 v3, 15, v0
	v_bfe_u32 v4, v0, 6, 1
	v_ashrrev_i32_e32 v5, 7, v0
	v_bfe_u32 v0, v0, 1, 3
	v_bitop3_b32 v1, v1, v0, 3 bitop3:0x6c
	v_bitop3_b32 v0, v2, v0, 4 bitop3:0x36
	v_lshlrev_b32_e32 v71, 4, v0
	v_lshlrev_b32_e32 v0, 2, v3
	v_readlane_b32 s0, v251, 30
	v_lshlrev_b32_e32 v6, 6, v5
	v_lshl_or_b32 v112, v4, 8, v0
	v_readlane_b32 s1, v251, 31
	s_mov_b32 s45, s39
	v_lshl_or_b32 v66, v2, 2, v6
	v_lshlrev_b32_e32 v67, 4, v1
	v_lshlrev_b32_e32 v68, 13, v5
	v_lshlrev_b32_e32 v69, 7, v3
	v_lshlrev_b32_e32 v70, 13, v4
	v_lshl_add_u64 v[64:65], s[0:1], 0, v[112:113]
	v_readlane_b32 s10, v250, 36
	v_readlane_b32 s1, v251, 20
	v_readlane_b32 s39, v251, 21
	v_readlane_b32 s44, v251, 22
